# v70 + grid barrier: non-leader workgroups poll the top-level generation word directly (one release hop less per barrier)
# baseline (speedup 1.0000x reference)
.LBB0_205:
	s_or_b64 exec, exec, s[38:39]
	v_cvt_f32_u32_e32 v4, v2
	s_waitcnt vmcnt(0)
	v_readfirstlane_b32 s2, v3
	v_sub_u32_e32 v3, 0, v2
	v_rcp_iflag_f32_e32 v4, v4
	v_add_u32_e32 v5, s2, v1
	v_mul_f32_e32 v4, 0x4f7ffffe, v4
	v_cvt_u32_f32_e32 v4, v4
	v_mul_lo_u32 v1, v3, v4
	v_mul_hi_u32 v1, v4, v1
	v_add_u32_e32 v1, v4, v1
	v_mul_hi_u32 v1, v5, v1
	v_mul_lo_u32 v3, v1, v2
	v_sub_u32_e32 v3, v5, v3
	v_add_u32_e32 v4, 1, v1
	v_sub_u32_e32 v6, v3, v2
	v_cmp_ge_u32_e32 vcc, v3, v2
	s_nop 1
	v_cndmask_b32_e32 v1, v1, v4, vcc
	v_cndmask_b32_e32 v3, v3, v6, vcc
	v_add_u32_e32 v4, 1, v1
	v_cmp_ge_u32_e32 vcc, v3, v2
	v_add_u32_e32 v3, 1, v5
	s_nop 0
	v_cndmask_b32_e32 v1, v1, v4, vcc
	v_mul_lo_u32 v4, v2, v1
	v_add_u32_e32 v2, v4, v2
	v_cmp_ne_u32_e32 vcc, v3, v2
	s_and_saveexec_b64 s[28:29], vcc
	s_xor_b64 s[38:39], exec, s[28:29]
	s_cbranch_execz .LBB0_219
	v_readlane_b32 s4, v253, 59
	v_readlane_b32 s5, v253, 60
	s_waitcnt lgkmcnt(0)
	s_nop 3
	global_load_dword v0, v143, s[4:5] sc1
	s_waitcnt vmcnt(0)
	v_cmp_eq_u32_e32 vcc, v0, v1
	s_and_saveexec_b64 s[40:41], vcc
	s_cbranch_execz .LBB0_218
	s_mov_b32 s2, 1
	s_mov_b64 s[42:43], 0
	s_branch .LBB0_209

.LBB0_211:
	v_readlane_b32 s4, v253, 59
	v_readlane_b32 s5, v253, 60
	s_add_i32 s2, s2, 1
	s_mov_b64 s[48:49], -1
	s_nop 2
	global_load_dword v0, v143, s[4:5] sc1
	s_waitcnt vmcnt(0)
	v_cmp_ne_u32_e32 vcc, v0, v1
	s_orn2_b64 s[46:47], vcc, exec
	s_branch .LBB0_208

.LBB0_325:
	s_or_b64 exec, exec, s[40:41]
	v_cvt_f32_u32_e32 v4, v2
	s_waitcnt vmcnt(0)
	v_readfirstlane_b32 s2, v3
	v_sub_u32_e32 v3, 0, v2
	v_rcp_iflag_f32_e32 v4, v4
	v_add_u32_e32 v5, s2, v1
	v_mul_f32_e32 v4, 0x4f7ffffe, v4
	v_cvt_u32_f32_e32 v4, v4
	v_mul_lo_u32 v1, v3, v4
	v_mul_hi_u32 v1, v4, v1
	v_add_u32_e32 v1, v4, v1
	v_mul_hi_u32 v1, v5, v1
	v_mul_lo_u32 v3, v1, v2
	v_sub_u32_e32 v3, v5, v3
	v_add_u32_e32 v4, 1, v1
	v_cmp_ge_u32_e32 vcc, v3, v2
	s_nop 1
	v_cndmask_b32_e32 v1, v1, v4, vcc
	v_sub_u32_e32 v4, v3, v2
	v_cndmask_b32_e32 v3, v3, v4, vcc
	v_add_u32_e32 v4, 1, v1
	v_cmp_ge_u32_e32 vcc, v3, v2
	v_add_u32_e32 v3, 1, v5
	s_nop 0
	v_cndmask_b32_e32 v1, v1, v4, vcc
	v_mul_lo_u32 v4, v2, v1
	v_add_u32_e32 v2, v4, v2
	v_cmp_ne_u32_e32 vcc, v3, v2
	s_and_saveexec_b64 s[28:29], vcc
	s_xor_b64 s[40:41], exec, s[28:29]
	s_cbranch_execz .LBB0_339
	v_readlane_b32 s4, v253, 59
	v_readlane_b32 s5, v253, 60
	s_waitcnt lgkmcnt(0)
	s_nop 3
	global_load_dword v0, v143, s[4:5] sc1
	s_waitcnt vmcnt(0)
	v_cmp_eq_u32_e32 vcc, v0, v1
	s_and_saveexec_b64 s[44:45], vcc
	s_cbranch_execz .LBB0_338
	s_mov_b32 s2, 1
	s_mov_b64 s[46:47], 0
	s_branch .LBB0_329

.LBB0_331:
	v_readlane_b32 s4, v253, 59
	v_readlane_b32 s5, v253, 60
	s_add_i32 s2, s2, 1
	s_mov_b64 s[52:53], -1
	s_nop 2
	global_load_dword v0, v143, s[4:5] sc1
	s_waitcnt vmcnt(0)
	v_cmp_ne_u32_e32 vcc, v0, v1
	s_orn2_b64 s[50:51], vcc, exec
	s_branch .LBB0_328

.LBB0_418:
	s_or_b64 exec, exec, s[40:41]
	v_cvt_f32_u32_e32 v4, v2
	s_waitcnt vmcnt(0)
	v_readfirstlane_b32 s2, v3
	v_sub_u32_e32 v3, 0, v2
	v_rcp_iflag_f32_e32 v4, v4
	v_add_u32_e32 v5, s2, v1
	v_mul_f32_e32 v4, 0x4f7ffffe, v4
	v_cvt_u32_f32_e32 v4, v4
	v_mul_lo_u32 v1, v3, v4
	v_mul_hi_u32 v1, v4, v1
	v_add_u32_e32 v1, v4, v1
	v_mul_hi_u32 v1, v5, v1
	v_mul_lo_u32 v3, v1, v2
	v_sub_u32_e32 v3, v5, v3
	v_add_u32_e32 v4, 1, v1
	v_cmp_ge_u32_e32 vcc, v3, v2
	s_nop 1
	v_cndmask_b32_e32 v1, v1, v4, vcc
	v_sub_u32_e32 v4, v3, v2
	v_cndmask_b32_e32 v3, v3, v4, vcc
	v_add_u32_e32 v4, 1, v1
	v_cmp_ge_u32_e32 vcc, v3, v2
	v_add_u32_e32 v3, 1, v5
	s_nop 0
	v_cndmask_b32_e32 v1, v1, v4, vcc
	v_mul_lo_u32 v4, v2, v1
	v_add_u32_e32 v2, v4, v2
	v_cmp_ne_u32_e32 vcc, v3, v2
	s_and_saveexec_b64 s[28:29], vcc
	s_xor_b64 s[40:41], exec, s[28:29]
	s_cbranch_execz .LBB0_432
	v_readlane_b32 s4, v253, 59
	v_readlane_b32 s5, v253, 60
	s_waitcnt lgkmcnt(0)
	s_nop 3
	global_load_dword v0, v143, s[4:5] sc1
	s_waitcnt vmcnt(0)
	v_cmp_eq_u32_e32 vcc, v0, v1
	s_and_saveexec_b64 s[42:43], vcc
	s_cbranch_execz .LBB0_431
	s_mov_b32 s2, 1
	s_mov_b64 s[46:47], 0
	s_branch .LBB0_422

.LBB0_572:
	s_or_b64 exec, exec, s[40:41]
	v_cvt_f32_u32_e32 v4, v2
	s_waitcnt vmcnt(0)
	v_readfirstlane_b32 s2, v3
	v_sub_u32_e32 v3, 0, v2
	v_rcp_iflag_f32_e32 v4, v4
	v_add_u32_e32 v5, s2, v1
	v_mul_f32_e32 v4, 0x4f7ffffe, v4
	v_cvt_u32_f32_e32 v4, v4
	v_mul_lo_u32 v1, v3, v4
	v_mul_hi_u32 v1, v4, v1
	v_add_u32_e32 v1, v4, v1
	v_mul_hi_u32 v1, v5, v1
	v_mul_lo_u32 v3, v1, v2
	v_sub_u32_e32 v3, v5, v3
	v_add_u32_e32 v4, 1, v1
	v_cmp_ge_u32_e32 vcc, v3, v2
	s_nop 1
	v_cndmask_b32_e32 v1, v1, v4, vcc
	v_sub_u32_e32 v4, v3, v2
	v_cndmask_b32_e32 v3, v3, v4, vcc
	v_add_u32_e32 v4, 1, v1
	v_cmp_ge_u32_e32 vcc, v3, v2
	v_add_u32_e32 v3, 1, v5
	s_nop 0
	v_cndmask_b32_e32 v1, v1, v4, vcc
	v_mul_lo_u32 v4, v2, v1
	v_add_u32_e32 v2, v4, v2
	v_cmp_ne_u32_e32 vcc, v3, v2
	s_and_saveexec_b64 s[28:29], vcc
	s_xor_b64 s[40:41], exec, s[28:29]
	s_cbranch_execz .LBB0_586
	v_readlane_b32 s4, v253, 59
	v_readlane_b32 s5, v253, 60
	s_waitcnt lgkmcnt(0)
	s_nop 3
	global_load_dword v0, v143, s[4:5] sc1
	s_waitcnt vmcnt(0)
	v_cmp_eq_u32_e32 vcc, v0, v1
	s_and_saveexec_b64 s[42:43], vcc
	s_cbranch_execz .LBB0_585
	s_mov_b32 s2, 1
	s_mov_b64 s[44:45], 0
	s_branch .LBB0_576

.LBB0_578:
	v_readlane_b32 s4, v253, 59
	v_readlane_b32 s5, v253, 60
	s_add_i32 s2, s2, 1
	s_mov_b64 s[50:51], -1
	s_nop 2
	global_load_dword v0, v143, s[4:5] sc1
	s_waitcnt vmcnt(0)
	v_cmp_ne_u32_e32 vcc, v0, v1
	s_orn2_b64 s[48:49], vcc, exec
	s_branch .LBB0_575

.LBB0_1183:
	s_or_b64 exec, exec, s[38:39]
	v_cvt_f32_u32_e32 v4, v2
	s_waitcnt vmcnt(0)
	v_readfirstlane_b32 s2, v3
	v_sub_u32_e32 v3, 0, v2
	v_rcp_iflag_f32_e32 v4, v4
	v_add_u32_e32 v5, s2, v1
	v_mul_f32_e32 v4, 0x4f7ffffe, v4
	v_cvt_u32_f32_e32 v4, v4
	v_mul_lo_u32 v1, v3, v4
	v_mul_hi_u32 v1, v4, v1
	v_add_u32_e32 v1, v4, v1
	v_mul_hi_u32 v1, v5, v1
	v_mul_lo_u32 v3, v1, v2
	v_sub_u32_e32 v3, v5, v3
	v_add_u32_e32 v4, 1, v1
	v_cmp_ge_u32_e32 vcc, v3, v2
	s_nop 1
	v_cndmask_b32_e32 v1, v1, v4, vcc
	v_sub_u32_e32 v4, v3, v2
	v_cndmask_b32_e32 v3, v3, v4, vcc
	v_add_u32_e32 v4, 1, v1
	v_cmp_ge_u32_e32 vcc, v3, v2
	v_add_u32_e32 v3, 1, v5
	s_nop 0
	v_cndmask_b32_e32 v1, v1, v4, vcc
	v_mul_lo_u32 v4, v2, v1
	v_add_u32_e32 v2, v4, v2
	v_cmp_ne_u32_e32 vcc, v3, v2
	s_and_saveexec_b64 s[28:29], vcc
	s_xor_b64 s[38:39], exec, s[28:29]
	s_cbranch_execz .LBB0_1197
	v_readlane_b32 s4, v253, 59
	v_readlane_b32 s5, v253, 60
	s_waitcnt lgkmcnt(0)
	s_nop 3
	global_load_dword v0, v143, s[4:5] sc1
	s_waitcnt vmcnt(0)
	v_cmp_eq_u32_e32 vcc, v0, v1
	s_and_saveexec_b64 s[40:41], vcc
	s_cbranch_execz .LBB0_1196
	s_mov_b32 s2, 1
	s_mov_b64 s[42:43], 0
	s_branch .LBB0_1187
